# idle w_o-GEMM workgroups prefetch the V rows of the sample memory-attention unit of their XCD after finishing (pure prefetch, values discarded)
# baseline (speedup 1.0000x reference)
; __device__ __forceinline__ int fresh_lane() { int l; asm volatile("v_mbcnt_lo_u32_b32 %0, -1, 0\n\tv_mbcnt_hi_u32_b32 %0, -1, %0" : "=v"(l)); return l; }
; __device__ __forceinline__ void memattn_unit(const Ctx& C, int r0, const float* kp0, const float* vp0, unsigned char* lds, int lane) {
;     ...
;         const float* vbase = vp0 + 128 * w + 2 * lane;
;         float2 va[16];
; #pragma unroll
;         for (int u = 0; u < 16; ++u) va[u] = *(const float2*)(vbase + (size_t)u * 1024);
; #pragma unroll 1
;         for (int m0 = 0; m0 < 256; m0 += 16) {
;             float2 vb[16];
;             const int mn = (m0 + 16 < 256) ? m0 + 16 : m0;
; #pragma unroll
;             for (int u = 0; u < 16; ++u) vb[u] = *(const float2*)(vbase + (size_t)(mn + u) * 1024);
; __global__ void __launch_bounds__(NTHREADS, 2) fwd(Args args) {
;     ...
;         const int wg0 = (C.G > DB) ? DB : 0;
;         if (C.bid < wg0 || wg0 == 0) for (int u = C.bid; u < DB; u += (wg0 ? wg0 : C.G)) memattn_unit(C, MP + u * 8, C.cmem_k + (size_t)u * 262144, C.cmem_v + (size_t)u * 262144, lds, fresh_lane());
;         if (C.bid >= wg0) {
;             pg8::Gemm g{(const bf16_t*)(ws + WS_OMEM), (const bf16_t*)(ws + WS_WO), MP, DM, DM, C.wave}; pg8::StaticOrder S; S.init(MP, DM, C.G - wg0, C.bid - wg0);
;             EpiRes E{nullptr, nullptr, (const bf16_t*)(ws + WS_H1B), nullptr, nullptr, (bf16_t*)(ws + WS_H2B), ss2};
;             pg8::gemm_phase<EpiRes, pg8::StaticOrder, true, true>(ldsl, g, S, E);
;         }
.LBB0_3255:
	s_waitcnt vmcnt(0)
	s_barrier
	s_sub_u32 s0, s84, 0x80
	s_lshr_b32 s1, s0, 12
	s_lshl_b32 s0, s0, 20
	v_readlane_b32 s2, v250, 23
	v_readlane_b32 s3, v250, 24
	s_add_u32 s2, s2, s0
	s_addc_u32 s3, s3, s1
	s_lshl_b32 s0, s76, 12
	s_add_u32 s0, s0, 0x20000
	s_add_u32 s2, s2, s0
	s_addc_u32 s3, s3, 0
	v_mbcnt_lo_u32_b32 v0, -1, 0
	v_mbcnt_hi_u32_b32 v0, -1, v0
	v_lshlrev_b32_e32 v0, 4, v0
	v_mov_b32_e32 v1, 0
	v_lshl_add_u64 v[2:3], s[2:3], 0, v[0:1]
	s_mov_b32 s4, 7
	s_mov_b32 s6, 0x8000
	s_mov_b32 s7, 0
.Lhelp_loop:
	global_load_dwordx4 v[4:7], v[2:3], off
	global_load_dwordx4 v[8:11], v[2:3], off offset:1024
	global_load_dwordx4 v[12:15], v[2:3], off offset:2048
	global_load_dwordx4 v[16:19], v[2:3], off offset:3072
	v_lshl_add_u64 v[2:3], v[2:3], 0, s[6:7]
	s_waitcnt vmcnt(12)
	global_load_dwordx4 v[20:23], v[2:3], off
	global_load_dwordx4 v[24:27], v[2:3], off offset:1024
	global_load_dwordx4 v[28:31], v[2:3], off offset:2048
	global_load_dwordx4 v[32:35], v[2:3], off offset:3072
	v_lshl_add_u64 v[2:3], v[2:3], 0, s[6:7]
	s_waitcnt vmcnt(12)
	global_load_dwordx4 v[36:39], v[2:3], off
	global_load_dwordx4 v[40:43], v[2:3], off offset:1024
	global_load_dwordx4 v[44:47], v[2:3], off offset:2048
	global_load_dwordx4 v[48:51], v[2:3], off offset:3072
	v_lshl_add_u64 v[2:3], v[2:3], 0, s[6:7]
	s_waitcnt vmcnt(12)
	global_load_dwordx4 v[52:55], v[2:3], off
	global_load_dwordx4 v[56:59], v[2:3], off offset:1024
	global_load_dwordx4 v[60:63], v[2:3], off offset:2048
	global_load_dwordx4 v[64:67], v[2:3], off offset:3072
	v_lshl_add_u64 v[2:3], v[2:3], 0, s[6:7]
	s_waitcnt vmcnt(12)
	s_sub_u32 s4, s4, 1
	s_cmp_lg_u32 s4, 0
	s_cbranch_scc1 .Lhelp_loop
